# static setprio 1 moved to waves 0-3 (instead of 4-7) in attention loops; mem-attention QK reads pipelined
# baseline (speedup 1.0000x reference)
; __device__ __forceinline__ int v_rd_base(int lane) { return ((lane & 3) << 3) | (((lane >> 2) & 3) << 6) | (((lane >> 4) & 1) << 5) | (((lane >> 5) & 1) << 8); }
; template <int LD>
; __device__ __forceinline__ void attn256_body(const bf16_t* __restrict__ Qb, const bf16_t* __restrict__ Kh, const unsigned char* __restrict__ Vimg, int seq, char* lds, LAS unsigned char* ldsl,
;                                              f32x16 (&o)[8], float (&rli)[16]) {
;   int tid = TIDX(); asm volatile("" : "+v"(tid));
;   const int wid = __builtin_amdgcn_readfirstlane(tid >> 6), lane = tid & 63, r32 = lane & 31, hi = lane >> 5;
;   float* wsf = (float*)(lds + LDS_XCH) + wid * 64; float* li_l = wsf; float* al_l = wsf + 32;
;   float m_reg = -1e30f, l_reg = 0.f; bf16x8 qr[8];
; #pragma unroll
;   for (int d = 0; d < 8; ++d) o[d] = f32x16{};
;   const bf16_t* Qw = Qb + (size_t)(wid * 32 + r32) * LD + hi * 8;
; #pragma unroll
;   for (int d0 = 0; d0 < 8; ++d0) qr[d0] = *(const bf16x8*)(Qw + d0 * 16);
;   unsigned voffK[2], voffV[2];
; #pragma unroll
;   for (int i = 0; i < 2; ++i) { const int b = (i * 512 + tid) * 16;
;     { const int row = b >> 8, cB = (b & 255) ^ ((row & 7) << 4); voffK[i] = (unsigned)(row * LD) * 2u + (unsigned)cB; }
;     { const int st = b >> 9, w = b & 511, kk = (st >> 2) * 8 + (w >> 6), c = (st & 3) * 32 + ((w & 63) >> 1);
;       (void)kk; (void)c; voffV[i] = (unsigned)tid * 16u; } }
;   const unsigned ldsw = (unsigned)wid * 1024u;
;     ...
;   const int NT = seq / 64;
;   const int vb0 = (int)(uintptr_t)lds + 16384 + v_rd_base(lane);
;   const int kbase = (int)(uintptr_t)lds + r32 * 256;
;   constexpr float C = ATT_SCALE * LOG2E;
;   __syncthreads();
;   A2_DMA(0, 0);
;   asm volatile("s_waitcnt vmcnt(0)" ::: "memory"); __syncthreads();
;   if (wid >= 4) __builtin_amdgcn_s_setprio(1);
.LBB0_659:
	s_getreg_b32 s0, hwreg(HW_REG_HW_ID, 0, 6)
	s_lshl_b32 s0, s0, 2
	s_and_b32 s0, s0, 0xfc
	s_add_i32 s0, s0, 0x24c40
	v_mov_b32_e32 v0, s0
	ds_read_b32 v0, v0
	s_lshl_b32 s0, s65, 5
	s_and_b32 s40, s0, 0xffffff00
	s_ashr_i32 s41, s40, 31
	s_and_b32 s4, s65, 7
	s_waitcnt lgkmcnt(0)
	v_readfirstlane_b32 s0, v0
	v_mbcnt_lo_u32_b32 v2, -1, 0
	v_mbcnt_hi_u32_b32 v2, -1, v2
	v_mov_b32_e32 v221, v1
	s_mov_b64 s[8:9], 0x100
	v_lshl_add_u32 v218, s0, 6, v2
	s_lshl_b64 s[0:1], s[40:41], 14
	s_add_u32 s0, s46, s0
	s_addc_u32 s1, s47, s1
	s_lshl_b32 s5, s4, 9
	s_add_u32 s34, s0, s5
	s_addc_u32 s35, s1, 0
	s_add_u32 s24, s95, s5
	v_readlane_b32 s0, v255, 10
	s_addc_u32 s25, s0, 0
	s_lshl_b32 s0, s4, 23
	s_add_u32 s12, s16, s0
	s_getreg_b32 s0, hwreg(HW_REG_HW_ID, 0, 6)
	s_addc_u32 s13, s17, 0
	s_lshl_b32 s0, s0, 2
	s_and_b32 s0, s0, 0xfc
	s_add_i32 s0, s0, 0x24c40
	v_mov_b32_e32 v0, s0
	ds_read_b32 v0, v0
	v_mbcnt_lo_u32_b32 v2, -1, 0
	v_mbcnt_hi_u32_b32 v2, -1, v2
	v_mov_b32_e32 v11, v1
	s_waitcnt lgkmcnt(0)
	v_readfirstlane_b32 s0, v0
	s_nop 1
	v_lshl_add_u32 v3, s0, 6, v2
	s_nop 0
	v_readfirstlane_b32 s5, v3
	s_ashr_i32 s6, s5, 6
	v_and_b32_e32 v4, 31, v3
	v_lshl_or_b32 v6, s6, 5, v4
	v_ashrrev_i32_e32 v7, 31, v6
	v_bfe_u32 v2, v3, 5, 1
	v_lshlrev_b64 v[6:7], 14, v[6:7]
	v_lshl_add_u64 v[6:7], s[34:35], 0, v[6:7]
	v_lshlrev_b32_e32 v220, 4, v2
	v_bfe_i32 v0, v3, 4, 24
	v_lshl_add_u64 v[6:7], v[6:7], 0, v[220:221]
	v_lshlrev_b32_e32 v14, 4, v3
	v_lshlrev_b32_e32 v8, 4, v0
	global_load_dwordx4 v[176:179], v[6:7], off offset:256
	global_load_dwordx4 v[180:183], v[6:7], off offset:288
	global_load_dwordx4 v[184:187], v[6:7], off offset:320
	global_load_dwordx4 v[188:191], v[6:7], off offset:352
	global_load_dwordx4 v[192:195], v[6:7], off offset:384
	global_load_dwordx4 v[196:199], v[6:7], off offset:416
	global_load_dwordx4 v[200:203], v[6:7], off offset:448
	global_load_dwordx4 v[204:207], v[6:7], off offset:480
	v_and_b32_e32 v7, 0xf0, v14
	v_and_b32_e32 v6, 0x70, v8
	v_lshlrev_b32_e32 v5, 14, v0
	v_bitop3_b32 v0, v6, v5, v7 bitop3:0xde
	v_add_u32_e32 v6, 0x2000, v14
	v_ashrrev_i32_e32 v6, 8, v6
	v_lshlrev_b32_e32 v9, 4, v6
	v_and_b32_e32 v10, 0x70, v9
	v_lshlrev_b32_e32 v6, 14, v6
	s_lshl_b32 s0, s6, 10
	v_bitop3_b32 v10, v10, v6, v7 bitop3:0xde
	s_add_i32 s0, s0, 0
	v_lshl_add_u64 v[12:13], s[24:25], 0, v[0:1]
	v_lshl_add_u64 v[12:13], v[12:13], 0, s[8:9]
	s_mov_b32 m0, s0
	v_lshl_add_u64 v[10:11], s[24:25], 0, v[10:11]
	s_barrier
	global_load_lds_dwordx4 v[12:13], off
	v_lshl_add_u64 v[10:11], v[10:11], 0, s[8:9]
	s_add_i32 m0, s0, 0x2000
	v_mov_b32_e32 v0, v14
	s_add_i32 s1, s0, 0x4000
	global_load_lds_dwordx4 v[10:11], off
	v_lshl_add_u64 v[10:11], s[12:13], 0, v[0:1]
	s_mov_b32 m0, s1
	s_add_i32 s28, s0, 0x6000
	global_load_lds_dwordx4 v14, s[12:13]
	v_lshl_add_u64 v[12:13], v[10:11], 0, s[54:55]
	s_mov_b32 m0, s28
	s_mov_b64 s[8:9], 0x4000
	s_add_i32 s29, s0, 0x8000
	global_load_lds_dwordx4 v[12:13], off
	v_lshl_add_u64 v[12:13], v[10:11], 0, s[8:9]
	s_mov_b32 m0, s29
	s_mov_b64 s[8:9], 0x6000
	s_add_i32 s52, s0, 0xa000
	global_load_lds_dwordx4 v[12:13], off
	v_lshl_add_u64 v[10:11], v[10:11], 0, s[8:9]
	s_mov_b32 m0, s52
	s_cmp_lt_i32 s6, 4
	global_load_lds_dwordx4 v[10:11], off
	s_waitcnt vmcnt(0)
	s_waitcnt vmcnt(0) lgkmcnt(0)
	s_barrier
	s_cbranch_scc0 .LBB0_661
	s_setprio 1

; #define LAS __attribute__((address_space(3)))
; __device__ __forceinline__ unsigned cvtpk(float lo, float hi) { unsigned r; asm volatile("v_cvt_pk_bf16_f32 %0, %1, %2" : "=v"(r) : "v"(lo), "v"(hi)); return r; }
; #define SBAR() __builtin_amdgcn_sched_barrier(0)
; __device__ __forceinline__ int crow(int r, int hi) { return (r & 3) + 8 * (r >> 2) + 4 * hi; }
; template <int LD>
; __device__ __forceinline__ void attn256_body(const bf16_t* __restrict__ Qb, const bf16_t* __restrict__ Kh, const unsigned char* __restrict__ Vimg, int seq, char* lds, LAS unsigned char* ldsl,
;                                              f32x16 (&o)[8], float (&rli)[16]) {
;     ...
;   __builtin_amdgcn_s_setprio(0);
;   if (hi == 0) li_l[r32] = l_reg; asm volatile("s_waitcnt lgkmcnt(0)" ::: "memory");
; #pragma unroll
;   for (int r = 0; r < 16; ++r) rli[r] = __builtin_amdgcn_rcpf(li_l[crow(r, hi)]);
;     ...
; }
; __device__ __forceinline__ void diff_item256(const Params& P, int h, int qb, float lam, char* lds, LAS unsigned char* ldsl) {
;   int tid = TIDX(); asm volatile("" : "+v"(tid));
;   const int wid = tid >> 6, lane = tid & 63, r32 = lane & 31, hi = lane >> 5;
;   bf16_t* proj = (bf16_t*)(P.ws + OFF_PROJ);
;   unsigned* scrw = (unsigned*)(P.ws + OFF_SCR) + (size_t)blockIdx.x * 32768;
;   f32x16 o[8]; float rli[16];
;   attn256_body<8192>(proj + (size_t)(qb * 256) * 8192 + 256 * h + 128, proj + 2048 + 256 * h + 128, P.ws + OFF_STATE + (size_t)h * 256 * 32768, TB, lds, ldsl, o, rli);
;   { unsigned* sp = scrw + tid; asm volatile("" : "+v"(sp));
; #pragma unroll
;     for (int d = 0; d < 8; ++d)
; #pragma unroll
;       for (int r = 0; r < 16; r += 2) { sp[(d * 8 + (r >> 1)) * 512] = cvtpk(o[d][r] * rli[r], o[d][r + 1] * rli[r + 1]); if (r == 14 && (d & 1)) SBAR(); } }
.LBB0_671:
	s_setprio 0
	s_and_saveexec_b64 s[44:45], s[38:39]
	ds_write_b32 v219, v2
	s_or_b64 exec, exec, s[44:45]
	s_waitcnt lgkmcnt(0)
	v_add_u32_e32 v0, s53, v220
	ds_read_b128 v[2:5], v0
	ds_read_b128 v[6:9], v0 offset:32
	v_readlane_b32 s0, v254, 43
	v_ashrrev_i32_e32 v219, 31, v218
	v_readlane_b32 s1, v254, 44
	s_waitcnt lgkmcnt(1)
	v_rcp_f32_e32 v10, v2
	v_rcp_f32_e32 v11, v3
	v_rcp_f32_e32 v12, v4
	v_rcp_f32_e32 v13, v5
	ds_read_b128 v[2:5], v0 offset:64
	v_lshl_add_u64 v[210:211], v[218:219], 2, s[0:1]
	s_waitcnt lgkmcnt(1)
	v_rcp_f32_e32 v14, v6
	v_rcp_f32_e32 v15, v7
	v_rcp_f32_e32 v144, v8
	v_rcp_f32_e32 v145, v9
	ds_read_b128 v[6:9], v0 offset:96
	s_waitcnt lgkmcnt(1)
	v_rcp_f32_e32 v0, v2
	v_rcp_f32_e32 v146, v3
	v_rcp_f32_e32 v147, v4
	v_mov_b64_e32 v[2:3], v[210:211]
	v_mul_f32_e32 v4, v128, v10
	v_rcp_f32_e32 v148, v5
	v_mul_f32_e32 v5, v129, v11
	v_cvt_pk_bf16_f32 v4, v4, v5
	flat_store_dword v[2:3], v4
	v_mul_f32_e32 v4, v130, v12
	v_mul_f32_e32 v5, v131, v13
	v_cvt_pk_bf16_f32 v4, v4, v5
	flat_store_dword v[2:3], v4 offset:2048
	v_mul_f32_e32 v4, v132, v14
	s_movk_i32 s0, 0x1000
	v_mul_f32_e32 v5, v133, v15
	v_cvt_pk_bf16_f32 v128, v4, v5
	v_add_co_u32_e32 v4, vcc, s0, v2
	s_waitcnt lgkmcnt(0)
	v_rcp_f32_e32 v6, v6
	v_addc_co_u32_e32 v5, vcc, 0, v3, vcc
	flat_store_dword v[4:5], v128
	v_mul_f32_e32 v128, v134, v144
	v_mul_f32_e32 v129, v135, v145
	v_cvt_pk_bf16_f32 v128, v128, v129
	flat_store_dword v[4:5], v128 offset:2048
	v_mul_f32_e32 v4, v136, v0
	s_movk_i32 s0, 0x2000
	v_rcp_f32_e32 v7, v7
	v_mul_f32_e32 v5, v137, v146
	v_cvt_pk_bf16_f32 v128, v4, v5
	v_add_co_u32_e32 v4, vcc, s0, v2
	v_rcp_f32_e32 v8, v8
	s_nop 0
	v_addc_co_u32_e32 v5, vcc, 0, v3, vcc
	flat_store_dword v[4:5], v128
	v_mul_f32_e32 v128, v138, v147
	v_rcp_f32_e32 v9, v9
	v_mul_f32_e32 v129, v139, v148
	v_cvt_pk_bf16_f32 v128, v128, v129
	flat_store_dword v[4:5], v128 offset:2048
	v_mul_f32_e32 v4, v140, v6
	v_mul_f32_e32 v5, v141, v7
	v_cvt_pk_bf16_f32 v128, v4, v5
	v_add_co_u32_e32 v4, vcc, s67, v2
	v_mul_f32_e32 v129, v143, v9
	s_nop 0
	v_addc_co_u32_e32 v5, vcc, 0, v3, vcc
	flat_store_dword v[4:5], v128
	v_mul_f32_e32 v128, v142, v8
	v_cvt_pk_bf16_f32 v128, v128, v129
	flat_store_dword v[4:5], v128 offset:2048
	v_mul_f32_e32 v4, v112, v10
	v_mul_f32_e32 v5, v113, v11
	v_cvt_pk_bf16_f32 v112, v4, v5
	v_add_co_u32_e32 v4, vcc, s66, v2
	v_mul_f32_e32 v113, v115, v13
	s_nop 0
	v_addc_co_u32_e32 v5, vcc, 0, v3, vcc
	flat_store_dword v[4:5], v112
	v_mul_f32_e32 v112, v114, v12
	v_cvt_pk_bf16_f32 v112, v112, v113
	flat_store_dword v[4:5], v112 offset:2048
	v_mul_f32_e32 v4, v116, v14
	s_movk_i32 s0, 0x5000
	v_mul_f32_e32 v5, v117, v15
	v_cvt_pk_bf16_f32 v112, v4, v5
	v_add_co_u32_e32 v4, vcc, s0, v2
	v_mul_f32_e32 v113, v119, v145
	s_nop 0
	v_addc_co_u32_e32 v5, vcc, 0, v3, vcc
	flat_store_dword v[4:5], v112
	v_mul_f32_e32 v112, v118, v144
	v_cvt_pk_bf16_f32 v112, v112, v113
	flat_store_dword v[4:5], v112 offset:2048
	v_mul_f32_e32 v4, v120, v0
	s_movk_i32 s0, 0x6000
	v_mul_f32_e32 v5, v121, v146
	v_cvt_pk_bf16_f32 v112, v4, v5
	v_add_co_u32_e32 v4, vcc, s0, v2
	v_mul_f32_e32 v113, v123, v148
	s_nop 0
	v_addc_co_u32_e32 v5, vcc, 0, v3, vcc
	flat_store_dword v[4:5], v112
	v_mul_f32_e32 v112, v122, v147
	v_cvt_pk_bf16_f32 v112, v112, v113
	flat_store_dword v[4:5], v112 offset:2048
	v_mul_f32_e32 v4, v124, v6
	s_movk_i32 s0, 0x7000
	v_mul_f32_e32 v5, v125, v7
	v_cvt_pk_bf16_f32 v112, v4, v5
	v_add_co_u32_e32 v4, vcc, s0, v2
	v_mul_f32_e32 v113, v127, v9
	s_nop 0
	v_addc_co_u32_e32 v5, vcc, 0, v3, vcc
	flat_store_dword v[4:5], v112
	v_mul_f32_e32 v112, v126, v8
	v_cvt_pk_bf16_f32 v112, v112, v113
	flat_store_dword v[4:5], v112 offset:2048
	v_mul_f32_e32 v4, v96, v10
	v_mul_f32_e32 v5, v97, v11
	v_cvt_pk_bf16_f32 v96, v4, v5
	v_add_co_u32_e32 v4, vcc, s88, v2
	v_mul_f32_e32 v97, v99, v13
	s_nop 0
	v_addc_co_u32_e32 v5, vcc, 0, v3, vcc
	flat_store_dword v[4:5], v96
	v_mul_f32_e32 v96, v98, v12
	v_cvt_pk_bf16_f32 v96, v96, v97
	flat_store_dword v[4:5], v96 offset:2048
	v_mul_f32_e32 v4, v100, v14
	s_mov_b32 s0, 0x9000
	v_mul_f32_e32 v5, v101, v15
	v_cvt_pk_bf16_f32 v96, v4, v5
	v_add_co_u32_e32 v4, vcc, s0, v2
	v_mul_f32_e32 v97, v103, v145
	s_nop 0
	v_addc_co_u32_e32 v5, vcc, 0, v3, vcc
	flat_store_dword v[4:5], v96
	v_mul_f32_e32 v96, v102, v144
	v_cvt_pk_bf16_f32 v96, v96, v97
	flat_store_dword v[4:5], v96 offset:2048
	v_mul_f32_e32 v4, v104, v0
	s_mov_b32 s0, 0xa000
	v_mul_f32_e32 v5, v105, v146
	v_cvt_pk_bf16_f32 v96, v4, v5
	v_add_co_u32_e32 v4, vcc, s0, v2
	v_mul_f32_e32 v97, v107, v148
	s_nop 0
	v_addc_co_u32_e32 v5, vcc, 0, v3, vcc
	flat_store_dword v[4:5], v96
	v_mul_f32_e32 v96, v106, v147
	v_cvt_pk_bf16_f32 v96, v96, v97
	flat_store_dword v[4:5], v96 offset:2048
	v_mul_f32_e32 v4, v108, v6
	s_mov_b32 s0, 0xb000
	v_mul_f32_e32 v5, v109, v7
	v_cvt_pk_bf16_f32 v96, v4, v5
	v_add_co_u32_e32 v4, vcc, s0, v2
	v_mul_f32_e32 v97, v111, v9
	s_nop 0
	v_addc_co_u32_e32 v5, vcc, 0, v3, vcc
	flat_store_dword v[4:5], v96
	v_mul_f32_e32 v96, v110, v8
	v_cvt_pk_bf16_f32 v96, v96, v97
	flat_store_dword v[4:5], v96 offset:2048
	v_mul_f32_e32 v4, v80, v10
	s_mov_b32 s0, 0xc000
	v_mul_f32_e32 v5, v81, v11
	v_cvt_pk_bf16_f32 v80, v4, v5
	v_add_co_u32_e32 v4, vcc, s0, v2
	v_mul_f32_e32 v81, v83, v13
	s_nop 0
	v_addc_co_u32_e32 v5, vcc, 0, v3, vcc
	flat_store_dword v[4:5], v80
	v_mul_f32_e32 v80, v82, v12
	v_cvt_pk_bf16_f32 v80, v80, v81
	flat_store_dword v[4:5], v80 offset:2048
	v_mul_f32_e32 v4, v84, v14
	s_mov_b32 s0, 0xd000
	v_mul_f32_e32 v5, v85, v15
	v_cvt_pk_bf16_f32 v80, v4, v5
	v_add_co_u32_e32 v4, vcc, s0, v2
	v_mul_f32_e32 v81, v87, v145
	s_nop 0
; __device__ __forceinline__ unsigned cvtpk(float lo, float hi) { unsigned r; asm volatile("v_cvt_pk_bf16_f32 %0, %1, %2" : "=v"(r) : "v"(lo), "v"(hi)); return r; }
; #define SBAR() __builtin_amdgcn_sched_barrier(0)
; __device__ __forceinline__ void diff_item256(const Params& P, int h, int qb, float lam, char* lds, LAS unsigned char* ldsl) {
;     ...
;   { unsigned* sp = scrw + tid; asm volatile("" : "+v"(sp));
; #pragma unroll
;     for (int d = 0; d < 8; ++d)
; #pragma unroll
;       for (int r = 0; r < 16; r += 2) { sp[(d * 8 + (r >> 1)) * 512] = cvtpk(o[d][r] * rli[r], o[d][r + 1] * rli[r + 1]); if (r == 14 && (d & 1)) SBAR(); } }
;   attn256_body<8192>(proj + (size_t)(qb * 256) * 8192 + 256 * h, proj + 2048 + 256 * h, P.ws + OFF_STATE + (size_t)h * 256 * 32768, TB, lds, ldsl, o, rli);
	v_addc_co_u32_e32 v5, vcc, 0, v3, vcc
	flat_store_dword v[4:5], v80
	v_mul_f32_e32 v80, v86, v144
	v_cvt_pk_bf16_f32 v80, v80, v81
	flat_store_dword v[4:5], v80 offset:2048
	v_mul_f32_e32 v4, v88, v0
	v_mul_f32_e32 v5, v89, v146
	v_cvt_pk_bf16_f32 v80, v4, v5
	v_add_co_u32_e32 v4, vcc, s89, v2
	v_mul_f32_e32 v81, v91, v148
	s_nop 0
	v_addc_co_u32_e32 v5, vcc, 0, v3, vcc
	flat_store_dword v[4:5], v80
	v_mul_f32_e32 v80, v90, v147
	v_cvt_pk_bf16_f32 v80, v80, v81
	flat_store_dword v[4:5], v80 offset:2048
	v_mul_f32_e32 v4, v92, v6
	s_mov_b32 s0, 0xf000
	v_mul_f32_e32 v5, v93, v7
	v_cvt_pk_bf16_f32 v80, v4, v5
	v_add_co_u32_e32 v4, vcc, s0, v2
	v_mul_f32_e32 v81, v95, v9
	s_nop 0
	v_addc_co_u32_e32 v5, vcc, 0, v3, vcc
	flat_store_dword v[4:5], v80
	v_mul_f32_e32 v80, v94, v8
	v_cvt_pk_bf16_f32 v80, v80, v81
	flat_store_dword v[4:5], v80 offset:2048
	v_mul_f32_e32 v4, v64, v10
	v_mul_f32_e32 v5, v65, v11
	v_cvt_pk_bf16_f32 v64, v4, v5
	v_add_co_u32_e32 v4, vcc, s90, v2
	v_mul_f32_e32 v65, v67, v13
	s_nop 0
	v_addc_co_u32_e32 v5, vcc, 0, v3, vcc
	flat_store_dword v[4:5], v64
	v_mul_f32_e32 v64, v66, v12
	v_cvt_pk_bf16_f32 v64, v64, v65
	flat_store_dword v[4:5], v64 offset:2048
	v_mul_f32_e32 v4, v68, v14
	s_mov_b32 s0, 0x11000
	v_mul_f32_e32 v5, v69, v15
	v_cvt_pk_bf16_f32 v64, v4, v5
	v_add_co_u32_e32 v4, vcc, s0, v2
	v_mul_f32_e32 v65, v71, v145
	s_nop 0
	v_addc_co_u32_e32 v5, vcc, 0, v3, vcc
	flat_store_dword v[4:5], v64
	v_mul_f32_e32 v64, v70, v144
	v_cvt_pk_bf16_f32 v64, v64, v65
	flat_store_dword v[4:5], v64 offset:2048
	v_mul_f32_e32 v4, v72, v0
	s_mov_b32 s0, 0x12000
	v_mul_f32_e32 v5, v73, v146
	v_cvt_pk_bf16_f32 v64, v4, v5
	v_add_co_u32_e32 v4, vcc, s0, v2
	v_mul_f32_e32 v65, v75, v148
	s_nop 0
	v_addc_co_u32_e32 v5, vcc, 0, v3, vcc
	flat_store_dword v[4:5], v64
	v_mul_f32_e32 v64, v74, v147
	v_cvt_pk_bf16_f32 v64, v64, v65
	flat_store_dword v[4:5], v64 offset:2048
	v_mul_f32_e32 v4, v76, v6
	s_mov_b32 s0, 0x13000
	v_mul_f32_e32 v5, v77, v7
	v_cvt_pk_bf16_f32 v64, v4, v5
	v_add_co_u32_e32 v4, vcc, s0, v2
	v_mul_f32_e32 v65, v79, v9
	s_nop 0
	v_addc_co_u32_e32 v5, vcc, 0, v3, vcc
	flat_store_dword v[4:5], v64
	v_mul_f32_e32 v64, v78, v8
	v_cvt_pk_bf16_f32 v64, v64, v65
	flat_store_dword v[4:5], v64 offset:2048
	v_mul_f32_e32 v4, v48, v10
	s_mov_b32 s0, 0x14000
	v_mul_f32_e32 v5, v49, v11
	v_cvt_pk_bf16_f32 v48, v4, v5
	v_add_co_u32_e32 v4, vcc, s0, v2
	v_mul_f32_e32 v49, v51, v13
	s_nop 0
	v_addc_co_u32_e32 v5, vcc, 0, v3, vcc
	flat_store_dword v[4:5], v48
	v_mul_f32_e32 v48, v50, v12
	v_cvt_pk_bf16_f32 v48, v48, v49
	flat_store_dword v[4:5], v48 offset:2048
	v_mul_f32_e32 v4, v52, v14
	s_mov_b32 s0, 0x15000
	v_mul_f32_e32 v5, v53, v15
	v_cvt_pk_bf16_f32 v48, v4, v5
	v_add_co_u32_e32 v4, vcc, s0, v2
	v_mul_f32_e32 v49, v55, v145
	s_nop 0
	v_addc_co_u32_e32 v5, vcc, 0, v3, vcc
	flat_store_dword v[4:5], v48
	v_mul_f32_e32 v48, v54, v144
	v_cvt_pk_bf16_f32 v48, v48, v49
	flat_store_dword v[4:5], v48 offset:2048
	v_mul_f32_e32 v4, v56, v0
	s_mov_b32 s0, 0x16000
	v_mul_f32_e32 v5, v57, v146
	v_cvt_pk_bf16_f32 v48, v4, v5
	v_add_co_u32_e32 v4, vcc, s0, v2
	v_mul_f32_e32 v49, v59, v148
	s_nop 0
	v_addc_co_u32_e32 v5, vcc, 0, v3, vcc
	flat_store_dword v[4:5], v48
	v_mul_f32_e32 v48, v58, v147
	v_cvt_pk_bf16_f32 v48, v48, v49
	flat_store_dword v[4:5], v48 offset:2048
	v_mul_f32_e32 v4, v60, v6
	s_mov_b32 s0, 0x17000
	v_mul_f32_e32 v5, v61, v7
	v_cvt_pk_bf16_f32 v48, v4, v5
	v_add_co_u32_e32 v4, vcc, s0, v2
	v_mul_f32_e32 v49, v63, v9
	s_nop 0
	v_addc_co_u32_e32 v5, vcc, 0, v3, vcc
	flat_store_dword v[4:5], v48
	v_mul_f32_e32 v48, v62, v8
	v_cvt_pk_bf16_f32 v48, v48, v49
	flat_store_dword v[4:5], v48 offset:2048
	v_mul_f32_e32 v4, v32, v10
	v_mul_f32_e32 v5, v33, v11
	v_cvt_pk_bf16_f32 v32, v4, v5
	v_add_co_u32_e32 v4, vcc, s20, v2
	v_mul_f32_e32 v33, v35, v13
	s_nop 0
	v_addc_co_u32_e32 v5, vcc, 0, v3, vcc
	flat_store_dword v[4:5], v32
	v_mul_f32_e32 v32, v34, v12
	v_cvt_pk_bf16_f32 v32, v32, v33
	flat_store_dword v[4:5], v32 offset:2048
	v_mul_f32_e32 v4, v36, v14
	s_mov_b32 s0, 0x19000
	v_mul_f32_e32 v5, v37, v15
	v_cvt_pk_bf16_f32 v32, v4, v5
	v_add_co_u32_e32 v4, vcc, s0, v2
	v_mul_f32_e32 v33, v39, v145
	s_nop 0
	v_addc_co_u32_e32 v5, vcc, 0, v3, vcc
	flat_store_dword v[4:5], v32
	v_mul_f32_e32 v32, v38, v144
	v_cvt_pk_bf16_f32 v32, v32, v33
	flat_store_dword v[4:5], v32 offset:2048
	v_mul_f32_e32 v4, v40, v0
	s_mov_b32 s0, 0x1a000
	v_mul_f32_e32 v5, v41, v146
	v_cvt_pk_bf16_f32 v32, v4, v5
	v_add_co_u32_e32 v4, vcc, s0, v2
	v_mul_f32_e32 v33, v43, v148
	s_nop 0
	v_addc_co_u32_e32 v5, vcc, 0, v3, vcc
	flat_store_dword v[4:5], v32
	v_mul_f32_e32 v32, v42, v147
	v_cvt_pk_bf16_f32 v32, v32, v33
	flat_store_dword v[4:5], v32 offset:2048
	v_mul_f32_e32 v4, v44, v6
	s_mov_b32 s0, 0x1b000
	v_mul_f32_e32 v5, v45, v7
	v_cvt_pk_bf16_f32 v32, v4, v5
	v_add_co_u32_e32 v4, vcc, s0, v2
	v_mul_f32_e32 v33, v47, v9
	s_nop 0
	v_addc_co_u32_e32 v5, vcc, 0, v3, vcc
	flat_store_dword v[4:5], v32
	v_mul_f32_e32 v32, v46, v8
	v_cvt_pk_bf16_f32 v32, v32, v33
	flat_store_dword v[4:5], v32 offset:2048
	v_mul_f32_e32 v4, v16, v10
	s_mov_b32 s0, 0x1c000
	v_mul_f32_e32 v5, v17, v11
	v_cvt_pk_bf16_f32 v10, v4, v5
	v_add_co_u32_e32 v4, vcc, s0, v2
	v_mul_f32_e32 v11, v19, v13
	s_nop 0
	v_addc_co_u32_e32 v5, vcc, 0, v3, vcc
	flat_store_dword v[4:5], v10
	v_mul_f32_e32 v10, v18, v12
	v_cvt_pk_bf16_f32 v10, v10, v11
	flat_store_dword v[4:5], v10 offset:2048
	v_mul_f32_e32 v4, v20, v14
	s_mov_b32 s0, 0x1d000
	v_mul_f32_e32 v5, v21, v15
	v_cvt_pk_bf16_f32 v10, v4, v5
	v_add_co_u32_e32 v4, vcc, s0, v2
	v_mul_f32_e32 v11, v23, v145
	s_nop 0
	v_addc_co_u32_e32 v5, vcc, 0, v3, vcc
	flat_store_dword v[4:5], v10
	v_mul_f32_e32 v10, v22, v144
	v_cvt_pk_bf16_f32 v10, v10, v11
	flat_store_dword v[4:5], v10 offset:2048
	v_mul_f32_e32 v0, v24, v0
	v_mul_f32_e32 v4, v25, v146
	s_mov_b32 s0, 0x1e000
	v_cvt_pk_bf16_f32 v0, v0, v4
	v_add_co_u32_e32 v4, vcc, s0, v2
	v_mul_f32_e32 v10, v27, v148
	s_nop 0
	v_addc_co_u32_e32 v5, vcc, 0, v3, vcc
	flat_store_dword v[4:5], v0
	v_mul_f32_e32 v0, v26, v147
	v_cvt_pk_bf16_f32 v0, v0, v10
	s_mov_b32 s0, 0x1f000
	flat_store_dword v[4:5], v0 offset:2048
	v_mul_f32_e32 v0, v28, v6
	v_add_co_u32_e32 v2, vcc, s0, v2
	v_mul_f32_e32 v4, v29, v7
	v_cvt_pk_bf16_f32 v0, v0, v4
	s_nop 0
	v_addc_co_u32_e32 v3, vcc, 0, v3, vcc
	flat_store_dword v[2:3], v0
	v_mul_f32_e32 v0, v30, v8
	v_mul_f32_e32 v4, v31, v9
	v_cvt_pk_bf16_f32 v0, v0, v4
	flat_store_dword v[2:3], v0 offset:2048
	s_getreg_b32 s0, hwreg(HW_REG_HW_ID, 0, 6)
	s_lshl_b32 s0, s0, 2
	s_and_b32 s0, s0, 0xfc
	s_add_i32 s0, s0, 0x24c40
	v_mov_b32_e32 v0, s0
	ds_read_b32 v0, v0
	v_mbcnt_lo_u32_b32 v2, -1, 0
	v_mbcnt_hi_u32_b32 v2, -1, v2
	v_mov_b32_e32 v221, v1
	s_mov_b64 s[6:7], 0x4000
	v_readlane_b32 s62, v255, 18
	s_waitcnt lgkmcnt(0)
; __device__ __forceinline__ int v_rd_base(int lane) { return ((lane & 3) << 3) | (((lane >> 2) & 3) << 6) | (((lane >> 4) & 1) << 5) | (((lane >> 5) & 1) << 8); }
; template <int LD>
; __device__ __forceinline__ void attn256_body(const bf16_t* __restrict__ Qb, const bf16_t* __restrict__ Kh, const unsigned char* __restrict__ Vimg, int seq, char* lds, LAS unsigned char* ldsl,
;                                              f32x16 (&o)[8], float (&rli)[16]) {
;   int tid = TIDX(); asm volatile("" : "+v"(tid));
;   const int wid = __builtin_amdgcn_readfirstlane(tid >> 6), lane = tid & 63, r32 = lane & 31, hi = lane >> 5;
;   float* wsf = (float*)(lds + LDS_XCH) + wid * 64; float* li_l = wsf; float* al_l = wsf + 32;
;   float m_reg = -1e30f, l_reg = 0.f; bf16x8 qr[8];
; #pragma unroll
;   for (int d = 0; d < 8; ++d) o[d] = f32x16{};
;   const bf16_t* Qw = Qb + (size_t)(wid * 32 + r32) * LD + hi * 8;
; #pragma unroll
;   for (int d0 = 0; d0 < 8; ++d0) qr[d0] = *(const bf16x8*)(Qw + d0 * 16);
;   unsigned voffK[2], voffV[2];
; #pragma unroll
;   for (int i = 0; i < 2; ++i) { const int b = (i * 512 + tid) * 16;
;     { const int row = b >> 8, cB = (b & 255) ^ ((row & 7) << 4); voffK[i] = (unsigned)(row * LD) * 2u + (unsigned)cB; }
;     { const int st = b >> 9, w = b & 511, kk = (st >> 2) * 8 + (w >> 6), c = (st & 3) * 32 + ((w & 63) >> 1);
;       (void)kk; (void)c; voffV[i] = (unsigned)tid * 16u; } }
;   const unsigned ldsw = (unsigned)wid * 1024u;
;     ...
;   const int NT = seq / 64;
;   const int vb0 = (int)(uintptr_t)lds + 16384 + v_rd_base(lane);
;   const int kbase = (int)(uintptr_t)lds + r32 * 256;
;   constexpr float C = ATT_SCALE * LOG2E;
;   __syncthreads();
;   A2_DMA(0, 0);
;   asm volatile("s_waitcnt vmcnt(0)" ::: "memory"); __syncthreads();
;   if (wid >= 4) __builtin_amdgcn_s_setprio(1);
	v_readfirstlane_b32 s0, v0
	v_readlane_b32 s63, v255, 19
	s_nop 0
	v_lshl_add_u32 v3, s0, 6, v2
	s_nop 0
	v_readfirstlane_b32 s4, v3
	v_and_b32_e32 v4, 31, v3
	s_ashr_i32 s5, s4, 6
	v_lshl_or_b32 v6, s5, 5, v4
	v_ashrrev_i32_e32 v7, 31, v6
	v_bfe_u32 v2, v3, 5, 1
	v_lshlrev_b64 v[6:7], 14, v[6:7]
	v_lshlrev_b32_e32 v220, 4, v2
	v_lshl_add_u64 v[6:7], s[34:35], 0, v[6:7]
	v_bfe_i32 v5, v3, 4, 24
	v_lshl_add_u64 v[6:7], v[6:7], 0, v[220:221]
	v_lshlrev_b32_e32 v0, 4, v3
	v_lshlrev_b32_e32 v8, 4, v5
	global_load_dwordx4 v[162:165], v[6:7], off
	global_load_dwordx4 v[166:169], v[6:7], off offset:32
	global_load_dwordx4 v[170:173], v[6:7], off offset:64
	global_load_dwordx4 v[174:177], v[6:7], off offset:96
	global_load_dwordx4 v[178:181], v[6:7], off offset:128
	global_load_dwordx4 v[182:185], v[6:7], off offset:160
	global_load_dwordx4 v[186:189], v[6:7], off offset:192
	global_load_dwordx4 v[190:193], v[6:7], off offset:224
	v_and_b32_e32 v7, 0xf0, v0
	v_and_b32_e32 v6, 0x70, v8
	v_lshlrev_b32_e32 v5, 14, v5
	v_bitop3_b32 v10, v6, v5, v7 bitop3:0xde
	v_add_u32_e32 v6, 0x2000, v0
	v_ashrrev_i32_e32 v6, 8, v6
	s_lshl_b32 s0, s5, 10
	v_lshlrev_b32_e32 v9, 4, v6
	s_add_i32 s0, s0, 0
	v_and_b32_e32 v11, 0x70, v9
	v_lshlrev_b32_e32 v6, 14, v6
	s_mov_b32 m0, s0
	v_bitop3_b32 v11, v11, v6, v7 bitop3:0xde
	s_waitcnt vmcnt(63) expcnt(7) lgkmcnt(15)
	s_barrier
	global_load_lds_dwordx4 v10, s[24:25]
	s_add_i32 m0, s0, 0x2000
	s_add_i32 s1, s0, 0x4000
	global_load_lds_dwordx4 v11, s[24:25]
	v_lshl_add_u64 v[10:11], s[12:13], 0, v[0:1]
	s_mov_b32 m0, s1
	s_add_i32 s24, s0, 0x6000
	global_load_lds_dwordx4 v0, s[12:13]
	v_lshl_add_u64 v[12:13], v[10:11], 0, s[54:55]
	s_mov_b32 m0, s24
	s_add_i32 s25, s0, 0x8000
	global_load_lds_dwordx4 v[12:13], off
	v_lshl_add_u64 v[12:13], v[10:11], 0, s[6:7]
	s_mov_b32 m0, s25
	s_mov_b64 s[6:7], 0x6000
	s_add_i32 s28, s0, 0xa000
	global_load_lds_dwordx4 v[12:13], off
	v_lshl_add_u64 v[10:11], v[10:11], 0, s[6:7]
	s_mov_b32 m0, s28
	s_cmp_lt_i32 s5, 4
	global_load_lds_dwordx4 v[10:11], off
	s_waitcnt vmcnt(0)
	s_waitcnt vmcnt(0) lgkmcnt(0)
	s_barrier
	s_cbranch_scc0 .LBB0_675
	s_setprio 1
